# P7 small-tile GEMM: register prefetch two K-steps ahead (second staging set v110-141), counted vmcnt(8)
# speedup vs baseline: 1.0102x; 1.0102x over previous
; #define SG_LOAD(k0) do { _Pragma("unroll") for (int i_ = 0; i_ < 4; ++i_) { const int id_ = tid + i_ * 512, rr_ = id_ >> 5, cc_ = id_ & 31; \
;         ra[i_] = *(const u32x4*)(Ag + (size_t)rr_ * lda + (k0) + cc_ * 8); rb[i_] = *(const u32x4*)(Bg + (size_t)rr_ * ldb + (k0) + cc_ * 8); } } while (0)
; template <class Epi>
; __device__ __forceinline__ void small_gemm_tile(unsigned char* lds, const bf16_t* A, int lda, const bf16_t* Bt, int ldb, int K, int kbreak, int rowbase, int tm, int tn, const Epi& E, int tid) {
;     ...
;     const bf16_t* Ag = A + (size_t)(rowbase + tm * 64) * lda; const bf16_t* Bg = Bt + (size_t)(tn * 64) * ldb;
;     u32x4 ra[4], rb[4];
;     ...
;     f32x4 cur[2], first[2];
; #pragma unroll
;     for (int n_ = 0; n_ < 2; ++n_) { cur[n_] = (f32x4){0.f, 0.f, 0.f, 0.f}; first[n_] = (f32x4){0.f, 0.f, 0.f, 0.f}; }
;     SG_LOAD(0);
.LBB0_1000:
	s_and_b32 s16, s25, 31
	s_lshl_b32 s16, s16, 20
	v_lshl_add_u64 v[66:67], v[56:57], 0, s[16:17]
	v_lshl_add_u64 v[68:69], v[58:59], 0, s[16:17]
	v_lshl_add_u64 v[70:71], v[60:61], 0, s[16:17]
	s_lshl_b32 s16, s26, 1
	s_andn2_b32 s16, s16, 63
	s_add_i32 s20, s16, 0x4000
	s_and_b32 s27, s26, 31
	s_ashr_i32 s21, s20, 31
	s_lshl_b64 s[22:23], s[20:21], 14
	s_lshl_b32 s16, s27, 20
	v_lshl_add_u64 v[16:17], v[42:43], 0, s[22:23]
	v_lshl_add_u64 v[18:19], v[44:45], 0, s[16:17]
	v_lshl_add_u64 v[8:9], v[16:17], 0, v[46:47]
	v_lshl_add_u64 v[10:11], v[18:19], 0, v[46:47]
	v_lshl_add_u64 v[20:21], v[16:17], 0, v[48:49]
	v_lshl_add_u64 v[22:23], v[18:19], 0, v[48:49]
	v_lshl_add_u64 v[28:29], v[16:17], 0, v[50:51]
	v_lshl_add_u64 v[30:31], v[18:19], 0, v[50:51]
	v_lshl_add_u64 v[16:17], v[16:17], 0, v[52:53]
	global_load_dwordx4 v[0:3], v[8:9], off
	global_load_dwordx4 v[4:7], v[10:11], off
	s_nop 0
	global_load_dwordx4 v[8:11], v[20:21], off
	global_load_dwordx4 v[12:15], v[22:23], off
	s_nop 0
	global_load_dwordx4 v[20:23], v[28:29], off
	global_load_dwordx4 v[24:27], v[30:31], off
	v_lshl_add_u64 v[18:19], v[18:19], 0, v[52:53]
	global_load_dwordx4 v[28:31], v[16:17], off
	global_load_dwordx4 v[32:35], v[18:19], off
	s_and_b32 s22, s3, 0xffffffc0
	s_ashr_i32 s23, s22, 31
	s_lshl_b64 s[22:23], s[22:23], 14
	v_lshl_add_u64 v[72:73], v[62:63], 0, s[22:23]
	v_lshl_add_u64 v[74:75], v[64:65], 0, s[22:23]
	v_lshl_add_u64 v[76:77], v[60:61], 0, s[22:23]
	s_mov_b32 s16, 0
	v_mov_b32_e32 v36, 0
	v_mov_b32_e32 v37, v41
	v_mov_b32_e32 v38, v41
	v_mov_b32_e32 v39, v41
	v_mov_b32_e32 v16, 0
	v_mov_b32_e32 v17, v41
	v_mov_b32_e32 v18, v41
	v_mov_b32_e32 v19, v41
	v_lshl_add_u64 v[126:127], v[76:77], 0, v[54:55]
	v_add_co_u32_e32 v110, vcc, 0x1c600000, v126
	v_lshl_add_u64 v[130:131], v[70:71], 0, v[54:55]
	s_nop 0
	v_addc_co_u32_e32 v111, vcc, 0, v127, vcc
	v_add_co_u32_e32 v114, vcc, 0x6400000, v130
	v_lshl_add_u64 v[118:119], v[74:75], 0, v[54:55]
	s_nop 0
	v_addc_co_u32_e32 v115, vcc, 0, v131, vcc
	v_add_co_u32_e32 v126, vcc, 0x1c680000, v126
	v_lshl_add_u64 v[122:123], v[68:69], 0, v[54:55]
	s_nop 0
	v_addc_co_u32_e32 v127, vcc, 0, v127, vcc
	v_add_co_u32_e32 v130, vcc, 0x6480000, v130
	v_lshl_add_u64 v[134:135], v[72:73], 0, v[54:55]
	s_nop 0
	v_addc_co_u32_e32 v131, vcc, 0, v131, vcc
	v_lshl_add_u64 v[138:139], v[66:67], 0, v[54:55]
	global_load_dwordx4 v[110:113], v[110:111], off offset:512
	s_nop 0
	global_load_dwordx4 v[114:117], v[114:115], off offset:512
	s_nop 0
	global_load_dwordx4 v[118:121], v[118:119], off
	s_nop 0
	global_load_dwordx4 v[122:125], v[122:123], off
	s_nop 0
	global_load_dwordx4 v[126:129], v[126:127], off offset:512
	s_nop 0
	global_load_dwordx4 v[130:133], v[130:131], off offset:512
	s_nop 0
	global_load_dwordx4 v[134:137], v[134:135], off
	s_nop 0
	global_load_dwordx4 v[138:141], v[138:139], off

; #define SG_LOAD(k0) do { _Pragma("unroll") for (int i_ = 0; i_ < 4; ++i_) { const int id_ = tid + i_ * 512, rr_ = id_ >> 5, cc_ = id_ & 31; \
;         ra[i_] = *(const u32x4*)(Ag + (size_t)rr_ * lda + (k0) + cc_ * 8); rb[i_] = *(const u32x4*)(Bg + (size_t)rr_ * ldb + (k0) + cc_ * 8); } } while (0)
; template <class Epi>
; __device__ __forceinline__ void small_gemm_tile(unsigned char* lds, const bf16_t* A, int lda, const bf16_t* Bt, int ldb, int K, int kbreak, int rowbase, int tm, int tn, const Epi& E, int tid) {
;     ...
;     SG_LOAD(0);
;     for (int k0 = 0; k0 < K; k0 += 256) {
	s_branch .Lp7s_e_head

; #define LBAR() asm volatile("s_waitcnt lgkmcnt(0)\n\ts_barrier" ::: "memory")
; #define SG_LOAD(k0) do { _Pragma("unroll") for (int i_ = 0; i_ < 4; ++i_) { const int id_ = tid + i_ * 512, rr_ = id_ >> 5, cc_ = id_ & 31; \
;         ra[i_] = *(const u32x4*)(Ag + (size_t)rr_ * lda + (k0) + cc_ * 8); rb[i_] = *(const u32x4*)(Bg + (size_t)rr_ * ldb + (k0) + cc_ * 8); } } while (0)
; template <class Epi>
; __device__ __forceinline__ void small_gemm_tile(unsigned char* lds, const bf16_t* A, int lda, const bf16_t* Bt, int ldb, int K, int kbreak, int rowbase, int tm, int tn, const Epi& E, int tid) {
;     ...
;     for (int k0 = 0; k0 < K; k0 += 256) {
; #pragma unroll
;         for (int i = 0; i < 4; ++i) { const int id = tid + i * 512, rr = id >> 5, cc = id & 31; *(u32x4*)(AS + rr * 528 + cc * 16) = ra[i]; *(u32x4*)(BS + rr * 528 + cc * 16) = rb[i]; }
;         LBAR();
;         if (k0 + 256 < K) SG_LOAD(k0 + 256);
.Lp7s_o_head:
	s_cmpk_lt_u32 s16, 0x1f00
	s_cbranch_scc1 .Lp7s_o_w8
	s_waitcnt vmcnt(0)
.Lp7s_o_w8:
	s_waitcnt vmcnt(8)
	ds_write_b128 v83, v[110:113]
	ds_write_b128 v83, v[114:117] offset:33792
	ds_write_b128 v84, v[118:121]
	ds_write_b128 v84, v[122:125] offset:33792
	ds_write_b128 v83, v[126:129] offset:16896
	ds_write_b128 v83, v[130:133] offset:50688
	ds_write_b128 v85, v[134:137]
	ds_write_b128 v85, v[138:141] offset:33792
	s_waitcnt lgkmcnt(0)
	s_barrier
	s_cmpk_gt_u32 s16, 0x1eff
	s_cselect_b64 s[22:23], -1, 0
	s_cmpk_lt_u32 s16, 0x1e00
	s_cbranch_scc0 .Lp7s_o_mma
	v_lshl_add_u64 v[126:127], v[76:77], 0, v[54:55]
	v_add_co_u32_e32 v110, vcc, 0x1c600000, v126
	v_lshl_add_u64 v[130:131], v[70:71], 0, v[54:55]
	s_nop 0
	v_addc_co_u32_e32 v111, vcc, 0, v127, vcc
	v_add_co_u32_e32 v114, vcc, 0x6400000, v130
	v_lshl_add_u64 v[118:119], v[74:75], 0, v[54:55]
	s_nop 0
	v_addc_co_u32_e32 v115, vcc, 0, v131, vcc
	v_add_co_u32_e32 v126, vcc, 0x1c680000, v126
	v_lshl_add_u64 v[122:123], v[68:69], 0, v[54:55]
	s_nop 0
	v_addc_co_u32_e32 v127, vcc, 0, v127, vcc
	v_add_co_u32_e32 v130, vcc, 0x6480000, v130
	v_lshl_add_u64 v[134:135], v[72:73], 0, v[54:55]
	s_nop 0
	v_addc_co_u32_e32 v131, vcc, 0, v131, vcc
	v_lshl_add_u64 v[138:139], v[66:67], 0, v[54:55]
	global_load_dwordx4 v[110:113], v[110:111], off offset:1024
	s_nop 0
	global_load_dwordx4 v[114:117], v[114:115], off offset:1024
	s_nop 0
	global_load_dwordx4 v[118:121], v[118:119], off offset:512
	s_nop 0
	global_load_dwordx4 v[122:125], v[122:123], off offset:512
	s_nop 0
	global_load_dwordx4 v[126:129], v[126:127], off offset:1024
	s_nop 0
	global_load_dwordx4 v[130:133], v[130:131], off offset:1024
	s_nop 0
	global_load_dwordx4 v[134:137], v[134:135], off offset:512
	s_nop 0
	global_load_dwordx4 v[138:141], v[138:139], off offset:512

; #define LBAR() asm volatile("s_waitcnt lgkmcnt(0)\n\ts_barrier" ::: "memory")
; #define SG_LOAD(k0) do { _Pragma("unroll") for (int i_ = 0; i_ < 4; ++i_) { const int id_ = tid + i_ * 512, rr_ = id_ >> 5, cc_ = id_ & 31; \
;         ra[i_] = *(const u32x4*)(Ag + (size_t)rr_ * lda + (k0) + cc_ * 8); rb[i_] = *(const u32x4*)(Bg + (size_t)rr_ * ldb + (k0) + cc_ * 8); } } while (0)
; template <class Epi>
; __device__ __forceinline__ void small_gemm_tile(unsigned char* lds, const bf16_t* A, int lda, const bf16_t* Bt, int ldb, int K, int kbreak, int rowbase, int tm, int tn, const Epi& E, int tid) {
;     ...
;     for (int k0 = 0; k0 < K; k0 += 256) {
; #pragma unroll
;         for (int i = 0; i < 4; ++i) { const int id = tid + i * 512, rr = id >> 5, cc = id & 31; *(u32x4*)(AS + rr * 528 + cc * 16) = ra[i]; *(u32x4*)(BS + rr * 528 + cc * 16) = rb[i]; }
;         LBAR();
;         if (k0 + 256 < K) SG_LOAD(k0 + 256);
;         if (k0 == kbreak) {
; #pragma unroll
;             for (int n_ = 0; n_ < 2; ++n_) { first[n_] = cur[n_]; cur[n_] = (f32x4){0.f, 0.f, 0.f, 0.f}; } }
; #pragma unroll
;         for (int kk = 0; kk < 8; ++kk) { const bf16x8 af = *(const bf16x8*)(AS + (wm * 16 + r16) * 528 + kk * 64 + q4 * 16);
; #pragma unroll
;             for (int nt = 0; nt < 2; ++nt) { const bf16x8 bfg = *(const bf16x8*)(BS + (wn * 32 + nt * 16 + r16) * 528 + kk * 64 + q4 * 16); cur[nt] = __builtin_amdgcn_mfma_f32_16x16x32_bf16(bfg, af, cur[nt], 0, 0, 0); } }
;         LBAR();
.Lp7s_o_mma:
	ds_read_b128 v[90:93], v87 offset:33792
	ds_read_b128 v[94:97], v86
	ds_read_b128 v[98:101], v86 offset:64
	ds_read_b128 v[102:105], v87 offset:33856
	s_addk_i32 s16, 0x100
	v_lshl_add_u64 v[66:67], v[66:67], 0, s[18:19]
	s_waitcnt lgkmcnt(2)
	v_mfma_f32_16x16x32_bf16 v[36:39], v[90:93], v[94:97], v[36:39]
	ds_read_b128 v[90:93], v87 offset:42240
	ds_read_b128 v[106:109], v87 offset:42304
	v_lshl_add_u64 v[68:69], v[68:69], 0, s[18:19]
	v_lshl_add_u64 v[70:71], v[70:71], 0, s[18:19]
	s_waitcnt lgkmcnt(1)
	v_mfma_f32_16x16x32_bf16 v[16:19], v[90:93], v[94:97], v[16:19]
	ds_read_b128 v[90:93], v87 offset:33920
	v_lshl_add_u64 v[72:73], v[72:73], 0, s[18:19]
	v_lshl_add_u64 v[74:75], v[74:75], 0, s[18:19]
	v_mfma_f32_16x16x32_bf16 v[36:39], v[102:105], v[98:101], v[36:39]
	v_lshl_add_u64 v[76:77], v[76:77], 0, s[18:19]
	s_and_b64 vcc, exec, s[22:23]
	s_waitcnt lgkmcnt(1)
	v_mfma_f32_16x16x32_bf16 v[16:19], v[106:109], v[98:101], v[16:19]
	ds_read_b128 v[94:97], v86 offset:128
	ds_read_b128 v[98:101], v86 offset:192
	ds_read_b128 v[102:105], v87 offset:33984
	s_waitcnt lgkmcnt(2)
	v_mfma_f32_16x16x32_bf16 v[36:39], v[90:93], v[94:97], v[36:39]
	ds_read_b128 v[90:93], v87 offset:42368
	ds_read_b128 v[106:109], v87 offset:42432
	s_waitcnt lgkmcnt(1)
	v_mfma_f32_16x16x32_bf16 v[16:19], v[90:93], v[94:97], v[16:19]
	ds_read_b128 v[90:93], v87 offset:34048
	v_mfma_f32_16x16x32_bf16 v[36:39], v[102:105], v[98:101], v[36:39]
	s_waitcnt lgkmcnt(1)
	v_mfma_f32_16x16x32_bf16 v[16:19], v[106:109], v[98:101], v[16:19]
	ds_read_b128 v[94:97], v86 offset:256
	ds_read_b128 v[98:101], v86 offset:320
	ds_read_b128 v[102:105], v87 offset:34112
	s_waitcnt lgkmcnt(2)
	v_mfma_f32_16x16x32_bf16 v[36:39], v[90:93], v[94:97], v[36:39]
	ds_read_b128 v[90:93], v87 offset:42496
	ds_read_b128 v[106:109], v87 offset:42560
	s_waitcnt lgkmcnt(1)
	v_mfma_f32_16x16x32_bf16 v[16:19], v[90:93], v[94:97], v[16:19]
	v_mfma_f32_16x16x32_bf16 v[36:39], v[102:105], v[98:101], v[36:39]
	ds_read_b128 v[90:93], v87 offset:34176
	ds_read_b128 v[94:97], v86 offset:384
	ds_read_b128 v[102:105], v87 offset:42624
	s_waitcnt lgkmcnt(3)
	v_mfma_f32_16x16x32_bf16 v[16:19], v[106:109], v[98:101], v[16:19]
	ds_read_b128 v[98:101], v86 offset:448
	ds_read_b128 v[106:109], v87 offset:34240
	s_waitcnt lgkmcnt(3)
	v_mfma_f32_16x16x32_bf16 v[36:39], v[90:93], v[94:97], v[36:39]
	ds_read_b128 v[90:93], v87 offset:42688
	s_waitcnt lgkmcnt(0)
	s_barrier
	s_waitcnt lgkmcnt(3)
	v_mfma_f32_16x16x32_bf16 v[16:19], v[102:105], v[94:97], v[16:19]
	s_waitcnt lgkmcnt(1)
	v_mfma_f32_16x16x32_bf16 v[36:39], v[106:109], v[98:101], v[36:39]
	s_waitcnt lgkmcnt(0)
	v_mfma_f32_16x16x32_bf16 v[16:19], v[90:93], v[98:101], v[16:19]
	s_cbranch_vccnz .LBB0_1004
	s_branch .Lp7s_e_head
.Lp7s_e_head:
	s_waitcnt vmcnt(8)
	ds_write_b128 v83, v[0:3]
	ds_write_b128 v83, v[4:7] offset:33792
	ds_write_b128 v84, v[8:11]
	ds_write_b128 v84, v[12:15] offset:33792
	ds_write_b128 v83, v[20:23] offset:16896
	ds_write_b128 v83, v[24:27] offset:50688
	ds_write_b128 v85, v[28:31]
	ds_write_b128 v85, v[32:35] offset:33792
	s_waitcnt lgkmcnt(0)
	s_barrier
	s_cmpk_gt_u32 s16, 0x1eff
	s_cselect_b64 s[22:23], -1, 0
	s_cmpk_lt_u32 s16, 0x1e00
	s_cbranch_scc0 .Lp7s_e_mma
	v_lshl_add_u64 v[20:21], v[76:77], 0, v[54:55]
	v_add_co_u32_e32 v0, vcc, 0x1c600000, v20
	v_lshl_add_u64 v[24:25], v[70:71], 0, v[54:55]
	s_nop 0
	v_addc_co_u32_e32 v1, vcc, 0, v21, vcc
	v_add_co_u32_e32 v4, vcc, 0x6400000, v24
	v_lshl_add_u64 v[8:9], v[74:75], 0, v[54:55]
	s_nop 0
	v_addc_co_u32_e32 v5, vcc, 0, v25, vcc
	v_add_co_u32_e32 v20, vcc, 0x1c680000, v20
	v_lshl_add_u64 v[12:13], v[68:69], 0, v[54:55]
	s_nop 0
	v_addc_co_u32_e32 v21, vcc, 0, v21, vcc
	v_add_co_u32_e32 v24, vcc, 0x6480000, v24
	v_lshl_add_u64 v[28:29], v[72:73], 0, v[54:55]
	s_nop 0
	v_addc_co_u32_e32 v25, vcc, 0, v25, vcc
	v_lshl_add_u64 v[32:33], v[66:67], 0, v[54:55]
	global_load_dwordx4 v[0:3], v[0:1], off offset:1024
	s_nop 0
	global_load_dwordx4 v[4:7], v[4:5], off offset:1024
	s_nop 0
	global_load_dwordx4 v[8:11], v[8:9], off offset:512
	s_nop 0
	global_load_dwordx4 v[12:15], v[12:13], off offset:512
	s_nop 0
	global_load_dwordx4 v[20:23], v[20:21], off offset:1024
	s_nop 0
	global_load_dwordx4 v[24:27], v[24:25], off offset:1024
	s_nop 0
	global_load_dwordx4 v[28:31], v[28:29], off offset:512
	s_nop 0
	global_load_dwordx4 v[32:35], v[32:33], off offset:512

; #define SG_LOAD(k0) do { _Pragma("unroll") for (int i_ = 0; i_ < 4; ++i_) { const int id_ = tid + i_ * 512, rr_ = id_ >> 5, cc_ = id_ & 31; \
;         ra[i_] = *(const u32x4*)(Ag + (size_t)rr_ * lda + (k0) + cc_ * 8); rb[i_] = *(const u32x4*)(Bg + (size_t)rr_ * ldb + (k0) + cc_ * 8); } } while (0)
; template <class Epi>
; __device__ __forceinline__ void small_gemm_tile(unsigned char* lds, const bf16_t* A, int lda, const bf16_t* Bt, int ldb, int K, int kbreak, int rowbase, int tm, int tn, const Epi& E, int tid) {
;     ...
;         if (k0 + 256 < K) SG_LOAD(k0 + 256);
;         if (k0 == kbreak) {
	s_branch .Lp7s_e_mma
